# attention kt loop rewritten by hand: S^T(g1) MFMAs issued under softmax(g0) VALU, P V(g0) under softmax(g1), K/V fragment reads two ahead
# speedup vs baseline: 1.0164x; 1.0164x over previous
; #define MFMA32(a, b, c) __builtin_amdgcn_mfma_f32_32x32x16_bf16((a), (b), (c), 0, 0, 0)
;     ...
;   for (int kt = 0; kt < nkt; ++kt) {
;     __syncthreads();
; #pragma unroll
;     for (int i = 0; i < 3; ++i) {
;       int c = tid + 256 * i, key = c / 12, part = c % 12;
;       *(u32x4*)(Ks + key * 104 + part * 8) = rk[i];
;     }
; #pragma unroll
;     for (int i = 0; i < 2; ++i) {
;       int c = tid + 256 * i, dv = c >> 3, part = c & 7;
;       *(u32x2*)(Vs + dv * 68 + part * 8) = mk2(rv[i].x, rv[i].y);
;       *(u32x2*)(Vs + dv * 68 + part * 8 + 4) = mk2(rv[i].z, rv[i].w);
;     }
;     __syncthreads();
;     if (kt + 1 < nkt) loadt(kt + 1);
;     f32x16 S[2][2];
; #pragma unroll
;     for (int g = 0; g < 2; ++g) { zero_acc(S[g][0]); zero_acc(S[g][1]); }
; #pragma unroll
;     for (int mt = 0; mt < 2; ++mt)
; #pragma unroll
;       for (int s = 0; s < 6; ++s) {
;         const bf16x8 a = *(const bf16x8*)(Ks + (mt * 32 + l31) * 104 + s * 16 + hh * 8);
;         S[0][mt] = MFMA32(a, qf[0][s], S[0][mt]);
;         S[1][mt] = MFMA32(a, qf[1][s], S[1][mt]);
;       }
;     asm volatile("s_nop 15\n\ts_nop 15" ::: "memory");
; #pragma unroll
;     for (int g = 0; g < 2; ++g) {
;       float mx = -1e30f;
; #pragma unroll
;       for (int mt = 0; mt < 2; ++mt)
; #pragma unroll
;         for (int r = 0; r < 16; ++r) mx = fmaxf(mx, S[g][mt][r]);
;       mx = fmaxf(mx, __shfl_xor(mx, 32)) * scl;
;       const float mnew = fmaxf(mrun[g], mx);
;       const float alpha = __builtin_amdgcn_exp2f(mrun[g] - mnew);
;       mrun[g] = mnew;
;       float ps = 0.f;
; #pragma unroll
;       for (int mt = 0; mt < 2; ++mt)
; #pragma unroll
;         for (int r = 0; r < 16; ++r) { float e = __builtin_amdgcn_exp2f(fmaf(S[g][mt][r], scl, -mnew)); S[g][mt][r] = e; ps += e; }
;       lsum[g] = lsum[g] * alpha + ps;
;       if (__builtin_amdgcn_ballot_w64(alpha != 1.f) != 0ull) {
; #pragma unroll
;         for (int d = 0; d < 2; ++d)
; #pragma unroll
;           for (int r = 0; r < 16; ++r) O[g][d][r] *= alpha;
;       }
.LBB0_1092:
	v_mov_b32_e32 v249, v216
	v_mov_b32_e32 v247, v250
	v_mov_b32_e32 v248, v251
	v_add_u32_e32 v214, 0x3000, v244
	v_add_u32_e32 v216, 0x3000, v245
	v_and_b32_e32 v221, 64, v219
	v_xor_b32_e32 v220, 32, v219
	v_add_u32_e32 v221, 64, v221
	v_cmp_lt_i32_e32 vcc, v220, v221
	s_nop 1
	v_cndmask_b32_e32 v220, v219, v220, vcc
	v_lshlrev_b32_e32 v237, 2, v220
.Latt_kt:
	v_lshl_add_u64 v[220:221], s[8:9], 0, v[212:213]
	s_barrier
	s_waitcnt vmcnt(4)
	ds_write_b128 v239, v[178:181]
	s_waitcnt vmcnt(3)
	ds_write_b128 v240, v[182:185]
	s_waitcnt vmcnt(2)
	ds_write_b128 v241, v[186:189]
	s_waitcnt vmcnt(1)
	ds_write2_b64 v242, v[190:191], v[192:193] offset1:1
	s_waitcnt vmcnt(0)
	ds_write2_b64 v243, v[194:195], v[196:197] offset1:1
	s_waitcnt lgkmcnt(0)
	s_barrier
	global_load_dwordx4 v[178:181], v[220:221], off
	v_lshl_add_u64 v[220:221], s[8:9], 0, v[210:211]
	global_load_dwordx4 v[182:185], v[220:221], off
	v_lshl_add_u64 v[220:221], s[8:9], 0, v[208:209]
	global_load_dwordx4 v[186:189], v[220:221], off
	v_lshl_add_u64 v[220:221], s[8:9], 0, v[206:207]
	global_load_dwordx4 v[190:193], v[220:221], off
	v_lshl_add_u64 v[220:221], s[8:9], 0, v[204:205]
	global_load_dwordx4 v[194:197], v[220:221], off
	ds_read_b128 v[220:223], v238
	ds_read_b128 v[224:227], v238 offset:6656
	ds_read_b128 v[230:233], v238 offset:32
	s_waitcnt lgkmcnt(2)
	v_mfma_f32_32x32x16_bf16 v[66:81], v[220:223], v[170:173], 0
	ds_read_b128 v[220:223], v238 offset:6688
	s_waitcnt lgkmcnt(2)
	v_mfma_f32_32x32x16_bf16 v[82:97], v[224:227], v[170:173], 0
	ds_read_b128 v[224:227], v238 offset:64
	s_waitcnt lgkmcnt(2)
	v_mfma_f32_32x32x16_bf16 v[66:81], v[230:233], v[158:161], v[66:81]
	ds_read_b128 v[230:233], v238 offset:6720
	s_waitcnt lgkmcnt(2)
	v_mfma_f32_32x32x16_bf16 v[82:97], v[220:223], v[158:161], v[82:97]
	ds_read_b128 v[220:223], v238 offset:96
	s_waitcnt lgkmcnt(2)
	v_mfma_f32_32x32x16_bf16 v[66:81], v[224:227], v[154:157], v[66:81]
	ds_read_b128 v[224:227], v238 offset:6752
	s_waitcnt lgkmcnt(2)
	v_mfma_f32_32x32x16_bf16 v[82:97], v[230:233], v[154:157], v[82:97]
	ds_read_b128 v[230:233], v238 offset:128
	s_waitcnt lgkmcnt(2)
	v_mfma_f32_32x32x16_bf16 v[66:81], v[220:223], v[142:145], v[66:81]
	ds_read_b128 v[220:223], v238 offset:6784
	s_waitcnt lgkmcnt(2)
	v_mfma_f32_32x32x16_bf16 v[82:97], v[224:227], v[142:145], v[82:97]
	ds_read_b128 v[224:227], v238 offset:160
	s_waitcnt lgkmcnt(2)
	v_mfma_f32_32x32x16_bf16 v[66:81], v[230:233], v[138:141], v[66:81]
	ds_read_b128 v[230:233], v238 offset:6816
	s_waitcnt lgkmcnt(2)
	v_mfma_f32_32x32x16_bf16 v[82:97], v[220:223], v[138:141], v[82:97]
	s_waitcnt lgkmcnt(1)
	v_mfma_f32_32x32x16_bf16 v[66:81], v[224:227], v[130:133], v[66:81]
	s_waitcnt lgkmcnt(0)
	v_mfma_f32_32x32x16_bf16 v[82:97], v[230:233], v[130:133], v[82:97]
	ds_read_b128 v[220:223], v238
	ds_read_b128 v[224:227], v238 offset:6656
	ds_read_b128 v[230:233], v238 offset:32
	s_waitcnt lgkmcnt(2)
	v_mfma_f32_32x32x16_bf16 v[98:113], v[220:223], v[174:177], 0
	ds_read_b128 v[220:223], v238 offset:6688
	s_waitcnt lgkmcnt(2)
	v_mfma_f32_32x32x16_bf16 v[114:129], v[224:227], v[174:177], 0
	s_nop 7
	v_max3_f32 v251, v66, s63, v67
	v_max3_f32 v251, v251, v68, v69
	v_max3_f32 v251, v251, v70, v71
	v_max3_f32 v251, v251, v72, v73
	v_max3_f32 v251, v251, v74, v75
	v_max3_f32 v251, v251, v76, v77
	v_max3_f32 v251, v251, v78, v79
	v_max3_f32 v251, v251, v80, v81
	v_max3_f32 v251, v251, v82, v83
	v_max3_f32 v251, v251, v84, v85
	v_max3_f32 v251, v251, v86, v87
	v_max3_f32 v251, v251, v88, v89
	v_max3_f32 v251, v251, v90, v91
	v_max3_f32 v251, v251, v92, v93
	ds_read_b128 v[224:227], v238 offset:64
	s_waitcnt lgkmcnt(2)
	v_mfma_f32_32x32x16_bf16 v[98:113], v[230:233], v[166:169], v[98:113]
	v_max3_f32 v251, v251, v94, v95
	v_max3_f32 v251, v251, v96, v97
	ds_bpermute_b32 v254, v237, v251
	s_waitcnt lgkmcnt(0)
	v_max_f32_e32 v254, v254, v254
	v_max_f32_e32 v251, v251, v254
	v_mul_f32_e32 v251, 0x3e16c740, v251
	v_max_f32_e32 v254, v246, v246
	v_max_f32_e32 v251, v254, v251
	v_sub_f32_e32 v236, v246, v251
	v_exp_f32_e32 v236, v236
	v_mov_b32_e32 v246, v251
	v_cmp_neq_f32_e32 vcc, 1.0, v236
	s_cbranch_vccz .Latt_noscale0
	v_pk_mul_f32 v[50:51], v[50:51], v[236:237] op_sel_hi:[1,0]
	v_pk_mul_f32 v[52:53], v[52:53], v[236:237] op_sel_hi:[1,0]
	v_pk_mul_f32 v[54:55], v[54:55], v[236:237] op_sel_hi:[1,0]
	v_pk_mul_f32 v[56:57], v[56:57], v[236:237] op_sel_hi:[1,0]
	v_pk_mul_f32 v[58:59], v[58:59], v[236:237] op_sel_hi:[1,0]
	v_pk_mul_f32 v[60:61], v[60:61], v[236:237] op_sel_hi:[1,0]
	v_pk_mul_f32 v[62:63], v[62:63], v[236:237] op_sel_hi:[1,0]
	v_pk_mul_f32 v[64:65], v[64:65], v[236:237] op_sel_hi:[1,0]
	v_pk_mul_f32 v[34:35], v[34:35], v[236:237] op_sel_hi:[1,0]
	v_pk_mul_f32 v[36:37], v[36:37], v[236:237] op_sel_hi:[1,0]
	v_pk_mul_f32 v[38:39], v[38:39], v[236:237] op_sel_hi:[1,0]
	v_pk_mul_f32 v[40:41], v[40:41], v[236:237] op_sel_hi:[1,0]
	v_pk_mul_f32 v[42:43], v[42:43], v[236:237] op_sel_hi:[1,0]
	v_pk_mul_f32 v[44:45], v[44:45], v[236:237] op_sel_hi:[1,0]
	v_pk_mul_f32 v[46:47], v[46:47], v[236:237] op_sel_hi:[1,0]
	v_pk_mul_f32 v[48:49], v[48:49], v[236:237] op_sel_hi:[1,0]
; #define MFMA32(a, b, c) __builtin_amdgcn_mfma_f32_32x32x16_bf16((a), (b), (c), 0, 0, 0)
; DI unsigned pack2(float lo, float hi) { f32x2 v; v.x = lo; v.y = hi; return __builtin_bit_cast(unsigned, __builtin_convertvector(v, hwbf2)); }
;     ...
; #pragma unroll
;     for (int g = 0; g < 2; ++g) {
;       float mx = -1e30f;
; #pragma unroll
;       for (int mt = 0; mt < 2; ++mt)
; #pragma unroll
;         for (int r = 0; r < 16; ++r) mx = fmaxf(mx, S[g][mt][r]);
;       mx = fmaxf(mx, __shfl_xor(mx, 32)) * scl;
;       const float mnew = fmaxf(mrun[g], mx);
;       const float alpha = __builtin_amdgcn_exp2f(mrun[g] - mnew);
;       mrun[g] = mnew;
;       float ps = 0.f;
; #pragma unroll
;       for (int mt = 0; mt < 2; ++mt)
; #pragma unroll
;         for (int r = 0; r < 16; ++r) { float e = __builtin_amdgcn_exp2f(fmaf(S[g][mt][r], scl, -mnew)); S[g][mt][r] = e; ps += e; }
;       lsum[g] = lsum[g] * alpha + ps;
;       if (__builtin_amdgcn_ballot_w64(alpha != 1.f) != 0ull) {
; #pragma unroll
;         for (int d = 0; d < 2; ++d)
; #pragma unroll
;           for (int r = 0; r < 16; ++r) O[g][d][r] *= alpha;
;       }
;     }
; #pragma unroll
;     for (int mt = 0; mt < 2; ++mt)
; #pragma unroll
;       for (int s2 = 0; s2 < 2; ++s2) {
;         bf16x8 pf[2];
; #pragma unroll
;         for (int g = 0; g < 2; ++g) {
;           unsigned pk[4];
; #pragma unroll
;           for (int q = 0; q < 4; ++q) pk[q] = pack2(S[g][mt][8 * s2 + 2 * q], S[g][mt][8 * s2 + 2 * q + 1]);
;           pf[g] = __builtin_bit_cast(bf16x8, (u32x4{pk[0], pk[1], pk[2], pk[3]}));
;         }
; #pragma unroll
;         for (int d = 0; d < 2; ++d) {
;           const u16* vp = Vs + (d * 32 + l31) * 68 + mt * 32 + s2 * 16 + 4 * hh;
;           u32x2 lo = *(const u32x2*)vp, hi = *(const u32x2*)(vp + 8);
;           const bf16x8 va = __builtin_bit_cast(bf16x8, (u32x4{lo.x, lo.y, hi.x, hi.y}));
;           O[0][d] = MFMA32(va, pf[0], O[0][d]);
;           O[1][d] = MFMA32(va, pf[1], O[1][d]);
;         }
;       }
.Latt_noscale0:
	v_fma_f32 v66, v66, s56, -v251
	v_exp_f32_e32 v66, v66
	ds_read_b128 v[230:233], v238 offset:6720
	v_mfma_f32_32x32x16_bf16 v[114:129], v[220:223], v[166:169], v[114:129]
	v_fma_f32 v67, v67, s56, -v251
	v_exp_f32_e32 v67, v67
	v_add_f32_e32 v254, 0, v66
	v_add_f32_e32 v254, v67, v254
	v_fma_f32 v68, v68, s56, -v251
	v_exp_f32_e32 v68, v68
	v_fma_f32 v69, v69, s56, -v251
	v_exp_f32_e32 v69, v69
	v_add_f32_e32 v254, v68, v254
	v_add_f32_e32 v254, v69, v254
	v_fma_f32 v70, v70, s56, -v251
	v_exp_f32_e32 v70, v70
	v_fma_f32 v71, v71, s56, -v251
	v_exp_f32_e32 v71, v71
	ds_read_b128 v[220:223], v238 offset:96
	v_mfma_f32_32x32x16_bf16 v[98:113], v[224:227], v[162:165], v[98:113]
	v_add_f32_e32 v254, v70, v254
	v_add_f32_e32 v254, v71, v254
	v_fma_f32 v72, v72, s56, -v251
	v_exp_f32_e32 v72, v72
	v_fma_f32 v73, v73, s56, -v251
	v_exp_f32_e32 v73, v73
	v_add_f32_e32 v254, v72, v254
	v_add_f32_e32 v254, v73, v254
	v_fma_f32 v74, v74, s56, -v251
	v_exp_f32_e32 v74, v74
	v_fma_f32 v75, v75, s56, -v251
	v_exp_f32_e32 v75, v75
	v_add_f32_e32 v254, v74, v254
	v_add_f32_e32 v254, v75, v254
	ds_read_b128 v[224:227], v238 offset:6752
	s_waitcnt lgkmcnt(2)
	v_mfma_f32_32x32x16_bf16 v[114:129], v[230:233], v[162:165], v[114:129]
	v_fma_f32 v76, v76, s56, -v251
	v_exp_f32_e32 v76, v76
	v_fma_f32 v77, v77, s56, -v251
	v_exp_f32_e32 v77, v77
	v_add_f32_e32 v254, v76, v254
	v_add_f32_e32 v254, v77, v254
	v_fma_f32 v78, v78, s56, -v251
	v_exp_f32_e32 v78, v78
	v_fma_f32 v79, v79, s56, -v251
	v_exp_f32_e32 v79, v79
	v_add_f32_e32 v254, v78, v254
	v_add_f32_e32 v254, v79, v254
	v_fma_f32 v80, v80, s56, -v251
	v_exp_f32_e32 v80, v80
	ds_read_b128 v[230:233], v238 offset:128
	s_waitcnt lgkmcnt(2)
	v_mfma_f32_32x32x16_bf16 v[98:113], v[220:223], v[150:153], v[98:113]
	v_fma_f32 v81, v81, s56, -v251
	v_exp_f32_e32 v81, v81
	v_add_f32_e32 v254, v80, v254
	v_add_f32_e32 v254, v81, v254
	v_fma_f32 v82, v82, s56, -v251
	v_exp_f32_e32 v82, v82
	v_fma_f32 v83, v83, s56, -v251
	v_exp_f32_e32 v83, v83
	v_add_f32_e32 v254, v82, v254
	v_add_f32_e32 v254, v83, v254
	v_fma_f32 v84, v84, s56, -v251
	v_exp_f32_e32 v84, v84
	v_fma_f32 v85, v85, s56, -v251
	v_exp_f32_e32 v85, v85
	ds_read_b128 v[220:223], v238 offset:6784
	s_waitcnt lgkmcnt(2)
	v_mfma_f32_32x32x16_bf16 v[114:129], v[224:227], v[150:153], v[114:129]
	v_add_f32_e32 v254, v84, v254
	v_add_f32_e32 v254, v85, v254
	v_fma_f32 v86, v86, s56, -v251
	v_exp_f32_e32 v86, v86
	v_fma_f32 v87, v87, s56, -v251
	v_exp_f32_e32 v87, v87
	v_add_f32_e32 v254, v86, v254
	v_add_f32_e32 v254, v87, v254
	v_fma_f32 v88, v88, s56, -v251
	v_exp_f32_e32 v88, v88
	v_fma_f32 v89, v89, s56, -v251
	v_exp_f32_e32 v89, v89
	v_add_f32_e32 v254, v88, v254
	v_add_f32_e32 v254, v89, v254
	ds_read_b128 v[224:227], v238 offset:160
	s_waitcnt lgkmcnt(2)
	v_mfma_f32_32x32x16_bf16 v[98:113], v[230:233], v[146:149], v[98:113]
	v_fma_f32 v90, v90, s56, -v251
	v_exp_f32_e32 v90, v90
	v_fma_f32 v91, v91, s56, -v251
	v_exp_f32_e32 v91, v91
	v_add_f32_e32 v254, v90, v254
	v_add_f32_e32 v254, v91, v254
	v_fma_f32 v92, v92, s56, -v251
	v_exp_f32_e32 v92, v92
	v_fma_f32 v93, v93, s56, -v251
	v_exp_f32_e32 v93, v93
	v_add_f32_e32 v254, v92, v254
	v_add_f32_e32 v254, v93, v254
	v_fma_f32 v94, v94, s56, -v251
	v_exp_f32_e32 v94, v94
	ds_read_b128 v[230:233], v238 offset:6816
	s_waitcnt lgkmcnt(2)
	v_mfma_f32_32x32x16_bf16 v[114:129], v[220:223], v[146:149], v[114:129]
	v_fma_f32 v95, v95, s56, -v251
	v_exp_f32_e32 v95, v95
	v_add_f32_e32 v254, v94, v254
	v_add_f32_e32 v254, v95, v254
	v_fma_f32 v96, v96, s56, -v251
	v_exp_f32_e32 v96, v96
	v_fma_f32 v97, v97, s56, -v251
	v_exp_f32_e32 v97, v97
	v_add_f32_e32 v254, v96, v254
	v_add_f32_e32 v254, v97, v254
	v_fmac_f32_e32 v254, v247, v236
	v_mov_b32_e32 v247, v254
	v_cvt_pk_bf16_f32 v66, v66, v67
	v_cvt_pk_bf16_f32 v67, v68, v69
	s_waitcnt lgkmcnt(1)
	v_mfma_f32_32x32x16_bf16 v[98:113], v[224:227], v[134:137], v[98:113]
	v_cvt_pk_bf16_f32 v68, v70, v71
	v_cvt_pk_bf16_f32 v69, v72, v73
	v_cvt_pk_bf16_f32 v70, v74, v75
	v_cvt_pk_bf16_f32 v71, v76, v77
	v_cvt_pk_bf16_f32 v72, v78, v79
	v_cvt_pk_bf16_f32 v73, v80, v81
	v_cvt_pk_bf16_f32 v74, v82, v83
	v_cvt_pk_bf16_f32 v75, v84, v85
	v_cvt_pk_bf16_f32 v76, v86, v87
	v_cvt_pk_bf16_f32 v77, v88, v89
	v_cvt_pk_bf16_f32 v78, v90, v91
	v_cvt_pk_bf16_f32 v79, v92, v93
	v_cvt_pk_bf16_f32 v80, v94, v95
	v_cvt_pk_bf16_f32 v81, v96, v97
	s_waitcnt lgkmcnt(0)
	v_mfma_f32_32x32x16_bf16 v[114:129], v[230:233], v[134:137], v[114:129]
	ds_read2_b64 v[220:223], v214 offset0:128 offset1:130
	ds_read2_b64 v[224:227], v216 offset0:128 offset1:130
	ds_read2_b64 v[230:233], v214 offset0:132 offset1:134
	s_waitcnt lgkmcnt(2)
	v_mfma_f32_32x32x16_bf16 v[50:65], v[220:223], v[66:69], v[50:65]
	s_nop 9
	v_max3_f32 v251, v98, s63, v99
	v_max3_f32 v251, v251, v100, v101
	v_max3_f32 v251, v251, v102, v103
	v_max3_f32 v251, v251, v104, v105
	v_max3_f32 v251, v251, v106, v107
	v_max3_f32 v251, v251, v108, v109
	v_max3_f32 v251, v251, v110, v111
	v_max3_f32 v251, v251, v112, v113
	v_max3_f32 v251, v251, v114, v115
	v_max3_f32 v251, v251, v116, v117
	v_max3_f32 v251, v251, v118, v119
	v_max3_f32 v251, v251, v120, v121
	v_max3_f32 v251, v251, v122, v123
	v_max3_f32 v251, v251, v124, v125
	v_max3_f32 v251, v251, v126, v127
	v_max3_f32 v251, v251, v128, v129
	ds_bpermute_b32 v254, v237, v251
	s_waitcnt lgkmcnt(0)
	v_max_f32_e32 v254, v254, v254
	v_max_f32_e32 v251, v251, v254
	v_mul_f32_e32 v251, 0x3e16c740, v251
	ds_read2_b64 v[220:223], v216 offset0:132 offset1:134
	v_mfma_f32_32x32x16_bf16 v[34:49], v[224:227], v[66:69], v[34:49]
	v_max_f32_e32 v254, v249, v249
	v_max_f32_e32 v251, v254, v251
	v_sub_f32_e32 v250, v249, v251
	v_exp_f32_e32 v250, v250
	v_mov_b32_e32 v249, v251
	v_cmp_neq_f32_e32 vcc, 1.0, v250
	s_cbranch_vccz .Latt_noscale1
	v_pk_mul_f32 v[18:19], v[18:19], v[250:251] op_sel_hi:[1,0]
	v_pk_mul_f32 v[20:21], v[20:21], v[250:251] op_sel_hi:[1,0]
	v_pk_mul_f32 v[22:23], v[22:23], v[250:251] op_sel_hi:[1,0]
	v_pk_mul_f32 v[24:25], v[24:25], v[250:251] op_sel_hi:[1,0]
	v_pk_mul_f32 v[26:27], v[26:27], v[250:251] op_sel_hi:[1,0]
	v_pk_mul_f32 v[28:29], v[28:29], v[250:251] op_sel_hi:[1,0]
	v_pk_mul_f32 v[30:31], v[30:31], v[250:251] op_sel_hi:[1,0]
	v_pk_mul_f32 v[32:33], v[32:33], v[250:251] op_sel_hi:[1,0]
	v_pk_mul_f32 v[2:3], v[2:3], v[250:251] op_sel_hi:[1,0]
	v_pk_mul_f32 v[4:5], v[4:5], v[250:251] op_sel_hi:[1,0]
	v_pk_mul_f32 v[6:7], v[6:7], v[250:251] op_sel_hi:[1,0]
	v_pk_mul_f32 v[8:9], v[8:9], v[250:251] op_sel_hi:[1,0]
	v_pk_mul_f32 v[10:11], v[10:11], v[250:251] op_sel_hi:[1,0]
	v_pk_mul_f32 v[12:13], v[12:13], v[250:251] op_sel_hi:[1,0]
	v_pk_mul_f32 v[14:15], v[14:15], v[250:251] op_sel_hi:[1,0]
	v_pk_mul_f32 v[16:17], v[16:17], v[250:251] op_sel_hi:[1,0]
; #define MFMA32(a, b, c) __builtin_amdgcn_mfma_f32_32x32x16_bf16((a), (b), (c), 0, 0, 0)
; DI unsigned pack2(float lo, float hi) { f32x2 v; v.x = lo; v.y = hi; return __builtin_bit_cast(unsigned, __builtin_convertvector(v, hwbf2)); }
;     ...
;       const float mnew = fmaxf(mrun[g], mx);
;       const float alpha = __builtin_amdgcn_exp2f(mrun[g] - mnew);
;       mrun[g] = mnew;
;       float ps = 0.f;
; #pragma unroll
;       for (int mt = 0; mt < 2; ++mt)
; #pragma unroll
;         for (int r = 0; r < 16; ++r) { float e = __builtin_amdgcn_exp2f(fmaf(S[g][mt][r], scl, -mnew)); S[g][mt][r] = e; ps += e; }
;       lsum[g] = lsum[g] * alpha + ps;
;       if (__builtin_amdgcn_ballot_w64(alpha != 1.f) != 0ull) {
; #pragma unroll
;         for (int d = 0; d < 2; ++d)
; #pragma unroll
;           for (int r = 0; r < 16; ++r) O[g][d][r] *= alpha;
;       }
;     }
; #pragma unroll
;     for (int mt = 0; mt < 2; ++mt)
; #pragma unroll
;       for (int s2 = 0; s2 < 2; ++s2) {
;         bf16x8 pf[2];
; #pragma unroll
;         for (int g = 0; g < 2; ++g) {
;           unsigned pk[4];
; #pragma unroll
;           for (int q = 0; q < 4; ++q) pk[q] = pack2(S[g][mt][8 * s2 + 2 * q], S[g][mt][8 * s2 + 2 * q + 1]);
;           pf[g] = __builtin_bit_cast(bf16x8, (u32x4{pk[0], pk[1], pk[2], pk[3]}));
;         }
; #pragma unroll
;         for (int d = 0; d < 2; ++d) {
;           const u16* vp = Vs + (d * 32 + l31) * 68 + mt * 32 + s2 * 16 + 4 * hh;
;           u32x2 lo = *(const u32x2*)vp, hi = *(const u32x2*)(vp + 8);
;           const bf16x8 va = __builtin_bit_cast(bf16x8, (u32x4{lo.x, lo.y, hi.x, hi.y}));
;           O[0][d] = MFMA32(va, pf[0], O[0][d]);
;           O[1][d] = MFMA32(va, pf[1], O[1][d]);
;         }
;       }
;     asm volatile("s_nop 15\n\ts_nop 15" ::: "memory");
.Latt_noscale1:
	v_fma_f32 v98, v98, s56, -v251
	v_exp_f32_e32 v98, v98
	v_fma_f32 v99, v99, s56, -v251
	v_exp_f32_e32 v99, v99
	v_add_f32_e32 v254, 0, v98
	v_add_f32_e32 v254, v99, v254
	v_fma_f32 v100, v100, s56, -v251
	v_exp_f32_e32 v100, v100
	v_fma_f32 v101, v101, s56, -v251
	v_exp_f32_e32 v101, v101
	v_add_f32_e32 v254, v100, v254
	v_add_f32_e32 v254, v101, v254
	v_fma_f32 v102, v102, s56, -v251
	v_exp_f32_e32 v102, v102
	v_fma_f32 v103, v103, s56, -v251
	ds_read2_b64 v[224:227], v214 offset0:136 offset1:138
	v_mfma_f32_32x32x16_bf16 v[50:65], v[230:233], v[70:73], v[50:65]
	v_exp_f32_e32 v103, v103
	v_add_f32_e32 v254, v102, v254
	v_add_f32_e32 v254, v103, v254
	v_fma_f32 v104, v104, s56, -v251
	v_exp_f32_e32 v104, v104
	v_fma_f32 v105, v105, s56, -v251
	v_exp_f32_e32 v105, v105
	v_add_f32_e32 v254, v104, v254
	v_add_f32_e32 v254, v105, v254
	v_fma_f32 v106, v106, s56, -v251
	v_exp_f32_e32 v106, v106
	v_fma_f32 v107, v107, s56, -v251
	v_exp_f32_e32 v107, v107
	v_add_f32_e32 v254, v106, v254
	v_add_f32_e32 v254, v107, v254
	v_fma_f32 v108, v108, s56, -v251
	v_exp_f32_e32 v108, v108
	v_fma_f32 v109, v109, s56, -v251
	v_exp_f32_e32 v109, v109
	v_add_f32_e32 v254, v108, v254
	v_add_f32_e32 v254, v109, v254
	ds_read2_b64 v[230:233], v216 offset0:136 offset1:138
	s_waitcnt lgkmcnt(2)
	v_mfma_f32_32x32x16_bf16 v[34:49], v[220:223], v[70:73], v[34:49]
	v_fma_f32 v110, v110, s56, -v251
	v_exp_f32_e32 v110, v110
	v_fma_f32 v111, v111, s56, -v251
	v_exp_f32_e32 v111, v111
	v_add_f32_e32 v254, v110, v254
	v_add_f32_e32 v254, v111, v254
	v_fma_f32 v112, v112, s56, -v251
	v_exp_f32_e32 v112, v112
	v_fma_f32 v113, v113, s56, -v251
	v_exp_f32_e32 v113, v113
	v_add_f32_e32 v254, v112, v254
	v_add_f32_e32 v254, v113, v254
	v_fma_f32 v114, v114, s56, -v251
	v_exp_f32_e32 v114, v114
	v_fma_f32 v115, v115, s56, -v251
	v_exp_f32_e32 v115, v115
	v_add_f32_e32 v254, v114, v254
	v_add_f32_e32 v254, v115, v254
	v_fma_f32 v116, v116, s56, -v251
	v_exp_f32_e32 v116, v116
	ds_read2_b64 v[220:223], v214 offset0:140 offset1:142
	s_waitcnt lgkmcnt(2)
	v_mfma_f32_32x32x16_bf16 v[50:65], v[224:227], v[74:77], v[50:65]
	v_fma_f32 v117, v117, s56, -v251
	v_exp_f32_e32 v117, v117
	v_add_f32_e32 v254, v116, v254
	v_add_f32_e32 v254, v117, v254
	v_fma_f32 v118, v118, s56, -v251
	v_exp_f32_e32 v118, v118
	v_fma_f32 v119, v119, s56, -v251
	v_exp_f32_e32 v119, v119
	v_add_f32_e32 v254, v118, v254
	v_add_f32_e32 v254, v119, v254
	v_fma_f32 v120, v120, s56, -v251
	v_exp_f32_e32 v120, v120
	v_fma_f32 v121, v121, s56, -v251
	v_exp_f32_e32 v121, v121
	v_add_f32_e32 v254, v120, v254
	v_add_f32_e32 v254, v121, v254
	v_fma_f32 v122, v122, s56, -v251
	v_exp_f32_e32 v122, v122
	v_fma_f32 v123, v123, s56, -v251
	v_exp_f32_e32 v123, v123
	v_add_f32_e32 v254, v122, v254
	ds_read2_b64 v[224:227], v216 offset0:140 offset1:142
	s_waitcnt lgkmcnt(2)
	v_mfma_f32_32x32x16_bf16 v[34:49], v[230:233], v[74:77], v[34:49]
	v_add_f32_e32 v254, v123, v254
	v_fma_f32 v124, v124, s56, -v251
	v_exp_f32_e32 v124, v124
	v_fma_f32 v125, v125, s56, -v251
	v_exp_f32_e32 v125, v125
	v_add_f32_e32 v254, v124, v254
	v_add_f32_e32 v254, v125, v254
	v_fma_f32 v126, v126, s56, -v251
	v_exp_f32_e32 v126, v126
	v_fma_f32 v127, v127, s56, -v251
	v_exp_f32_e32 v127, v127
	v_add_f32_e32 v254, v126, v254
	v_add_f32_e32 v254, v127, v254
	v_fma_f32 v128, v128, s56, -v251
	v_exp_f32_e32 v128, v128
	v_fma_f32 v129, v129, s56, -v251
	v_exp_f32_e32 v129, v129
	v_add_f32_e32 v254, v128, v254
	v_add_f32_e32 v254, v129, v254
	v_fmac_f32_e32 v254, v248, v250
	v_mov_b32_e32 v248, v254
	s_waitcnt lgkmcnt(1)
	v_mfma_f32_32x32x16_bf16 v[50:65], v[220:223], v[78:81], v[50:65]
	v_cvt_pk_bf16_f32 v98, v98, v99
	v_cvt_pk_bf16_f32 v99, v100, v101
	v_cvt_pk_bf16_f32 v100, v102, v103
	v_cvt_pk_bf16_f32 v101, v104, v105
	v_cvt_pk_bf16_f32 v102, v106, v107
	v_cvt_pk_bf16_f32 v103, v108, v109
	v_cvt_pk_bf16_f32 v104, v110, v111
	v_cvt_pk_bf16_f32 v105, v112, v113
	v_cvt_pk_bf16_f32 v106, v114, v115
	v_cvt_pk_bf16_f32 v107, v116, v117
	v_cvt_pk_bf16_f32 v108, v118, v119
	v_cvt_pk_bf16_f32 v109, v120, v121
	v_cvt_pk_bf16_f32 v110, v122, v123
	v_cvt_pk_bf16_f32 v111, v124, v125
	v_cvt_pk_bf16_f32 v112, v126, v127
	v_cvt_pk_bf16_f32 v113, v128, v129
	v_lshl_add_u64 v[204:205], v[204:205], 0, s[50:51]
	v_lshl_add_u64 v[206:207], v[206:207], 0, s[50:51]
	v_lshl_add_u64 v[208:209], v[208:209], 0, s[64:65]
	v_lshl_add_u64 v[210:211], v[210:211], 0, s[64:65]
	v_lshl_add_u64 v[212:213], v[212:213], 0, s[64:65]
	s_waitcnt lgkmcnt(0)
	v_mfma_f32_32x32x16_bf16 v[34:49], v[224:227], v[78:81], v[34:49]
	ds_read2_b64 v[220:223], v214 offset0:128 offset1:130
	ds_read2_b64 v[224:227], v216 offset0:128 offset1:130
	ds_read2_b64 v[230:233], v214 offset0:132 offset1:134
	s_waitcnt lgkmcnt(2)
	v_mfma_f32_32x32x16_bf16 v[18:33], v[220:223], v[98:101], v[18:33]
	ds_read2_b64 v[220:223], v216 offset0:132 offset1:134
	s_waitcnt lgkmcnt(2)
	v_mfma_f32_32x32x16_bf16 v[2:17], v[224:227], v[98:101], v[2:17]
	ds_read2_b64 v[224:227], v214 offset0:136 offset1:138
	s_waitcnt lgkmcnt(2)
	v_mfma_f32_32x32x16_bf16 v[18:33], v[230:233], v[102:105], v[18:33]
	ds_read2_b64 v[230:233], v216 offset0:136 offset1:138
	s_waitcnt lgkmcnt(2)
	v_mfma_f32_32x32x16_bf16 v[2:17], v[220:223], v[102:105], v[2:17]
	ds_read2_b64 v[220:223], v214 offset0:140 offset1:142
	s_waitcnt lgkmcnt(2)
	v_mfma_f32_32x32x16_bf16 v[18:33], v[224:227], v[106:109], v[18:33]
	ds_read2_b64 v[224:227], v216 offset0:140 offset1:142
	s_waitcnt lgkmcnt(2)
	v_mfma_f32_32x32x16_bf16 v[2:17], v[230:233], v[106:109], v[2:17]
	s_waitcnt lgkmcnt(1)
	v_mfma_f32_32x32x16_bf16 v[18:33], v[220:223], v[110:113], v[18:33]
	s_waitcnt lgkmcnt(0)
	v_mfma_f32_32x32x16_bf16 v[2:17], v[224:227], v[110:113], v[2:17]
	s_add_i32 s2, s2, -1
	s_cmp_eq_u32 s2, 0
	s_cbranch_scc0 .Latt_kt
	v_mov_b32_e32 v232, 0x47
